# baseline (speedup 1.0000x reference)
; template <int EPI> ...
;     ...
;   auto tile_desc = [&](int i, int& pm, int& pn, int& koff, bool& atom) {
;     koff = 0;
;     atom = false;
;     if (i < nA) {
;       tile_coords(startA + jA + i * perA, nM, nN, pm, pn);
;     } else {
;       int u = startB + jB + (i - nA) * perB;
;       pm = mini_pm;
;       pn = u % nN;
;       koff = (u / nN) * Kc;
;       atom = true;
;     }
;   };
.LBB0_182:
	s_cmp_ge_i32 s99, s95
	s_cselect_b64 s[82:83], -1, 0
	s_cmp_lt_i32 s99, s95
	s_mov_b64 s[40:41], -1
	s_cselect_b64 s[84:85], -1, 0
	s_and_b64 vcc, exec, s[82:83]
	s_cbranch_vccnz .LBB0_184
	s_mul_i32 s2, s99, s94
	s_add_i32 s2, s2, s58
	s_ashr_i32 s6, s2, 31
	s_lshr_b32 s6, s6, 28
	s_add_i32 s6, s2, s6
	s_ashr_i32 s7, s6, 4
	s_lshl_b32 s7, s7, 1
	s_sub_i32 s8, s77, s7
	s_min_i32 s8, s8, 2
	s_abs_i32 s9, s8
	v_cvt_f32_u32_e32 v0, s9
	s_sub_i32 s11, 0, s9
	s_andn2_b32 s6, s6, 15
	s_sub_i32 s6, s2, s6
	v_rcp_iflag_f32_e32 v0, v0
	s_abs_i32 s2, s6
	s_xor_b32 s10, s6, s8
	s_ashr_i32 s10, s10, 31
	v_mul_f32_e32 v0, 0x4f7ffffe, v0
	v_cvt_u32_f32_e32 v0, v0
	s_mov_b64 s[40:41], 0
	v_readfirstlane_b32 s20, v0
	s_mul_i32 s11, s11, s20
	s_mul_hi_u32 s11, s20, s11
	s_add_i32 s20, s20, s11
	s_mul_hi_u32 s11, s2, s20
	s_mul_i32 s20, s11, s9
	s_sub_i32 s2, s2, s20
	s_add_i32 s21, s11, 1
	s_sub_i32 s20, s2, s9
	s_cmp_ge_u32 s2, s9
	s_cselect_b32 s11, s21, s11
	s_cselect_b32 s2, s20, s2
	s_add_i32 s20, s11, 1
	s_cmp_ge_u32 s2, s9
	s_cselect_b32 s2, s20, s11
	s_xor_b32 s2, s2, s10
	s_sub_i32 s2, s2, s10
	s_mul_i32 s8, s2, s8
	s_sub_i32 s6, s6, s8
	s_add_i32 s7, s6, s7
	s_sub_i32 s7, s77, s7
	s_add_i32 s7, s7, -1

; template <int EPI> ...
;     ...
;   auto tile_desc = [&](int i, int& pm, int& pn, int& koff, bool& atom) {
;     koff = 0;
;     atom = false;
;     if (i < nA) {
;       tile_coords(startA + jA + i * perA, nM, nN, pm, pn);
;     } else {
;       int u = startB + jB + (i - nA) * perB;
;       pm = mini_pm;
;       pn = u % nN;
;       koff = (u / nN) * Kc;
;       atom = true;
;     }
;   };
.LBB0_191:
	s_andn2_b64 vcc, exec, s[50:51]
	s_mov_b32 s8, s56
	s_cbranch_vccnz .LBB0_193
	s_mul_i32 s7, s99, s94
	s_add_i32 s7, s7, s58
	s_ashr_i32 s8, s7, 31
	s_lshr_b32 s8, s8, 28
	s_add_i32 s8, s7, s8
	s_ashr_i32 s9, s8, 4
	s_lshl_b32 s9, s9, 1
	s_sub_i32 s10, s77, s9
	s_min_i32 s10, s10, 2
	s_abs_i32 s11, s10
	v_cvt_f32_u32_e32 v0, s11
	s_sub_i32 s21, 0, s11
	s_andn2_b32 s8, s8, 15
	s_sub_i32 s8, s7, s8
	v_rcp_iflag_f32_e32 v0, v0
	s_abs_i32 s7, s8
	s_xor_b32 s20, s8, s10
	s_ashr_i32 s20, s20, 31
	v_mul_f32_e32 v0, 0x4f7ffffe, v0
	v_cvt_u32_f32_e32 v0, v0
	s_mov_b64 s[40:41], 0
	v_readfirstlane_b32 s28, v0
	s_mul_i32 s21, s21, s28
	s_mul_hi_u32 s21, s28, s21
	s_add_i32 s28, s28, s21
	s_mul_hi_u32 s21, s7, s28
	s_mul_i32 s28, s21, s11
	s_sub_i32 s7, s7, s28
	s_add_i32 s29, s21, 1
	s_sub_i32 s28, s7, s11
	s_cmp_ge_u32 s7, s11
	s_cselect_b32 s21, s29, s21
	s_cselect_b32 s7, s28, s7
	s_add_i32 s28, s21, 1
	s_cmp_ge_u32 s7, s11
	s_cselect_b32 s7, s28, s21
	s_xor_b32 s7, s7, s20
	s_sub_i32 s7, s7, s20
	s_mul_i32 s10, s7, s10
	s_sub_i32 s8, s8, s10
	s_add_i32 s8, s8, s9
	s_sub_i32 s8, s77, s8
	s_add_i32 s8, s8, -1
